# scan compute loop: lgkmcnt waits used as DPP padding in five steps, back edge taken before the chunk barrier
# speedup vs baseline: 1.0024x; 1.0024x over previous
.Lscan_compute_entry:
	ds_read_b128 v[14:17], v0 offset:20480
	ds_read_b128 v[10:13], v0 offset:20496
	ds_read_b128 v[6:9], v0 offset:20512
	ds_read_b128 v[2:5], v0 offset:20528
	ds_read_b128 v[54:57], v89 offset:16384
	ds_read_b128 v[26:29], v89 offset:16640
	ds_read_b128 v[78:81], v89 offset:4096
	ds_read_b128 v[58:61], v89 offset:4352
	ds_read_b128 v[30:33], v89 offset:4608
	ds_read_b128 v[22:25], v90 offset:8704
	ds_read_b128 v[18:21], v89 offset:16896
	v_pk_mul_f32 v[66:67], v[74:75], v[108:109]
	s_waitcnt lgkmcnt(4)
	v_pk_mul_f32 v[78:79], v[14:15], v[78:79] op_sel_hi:[0,1]
	v_pk_fma_f32 v[66:67], v[76:77], v[110:111], v[66:67]
	v_pk_mul_f32 v[80:81], v[14:15], v[80:81] op_sel_hi:[0,1]
	v_add_f32_e32 v66, v66, v67
	v_pk_fma_f32 v[62:63], v[74:75], v[100:101], v[78:79]
	v_pk_fma_f32 v[64:65], v[76:77], v[102:103], v[80:81]
	v_add_f32_dpp v66, v66, v66 quad_perm:[1,0,3,2] row_mask:0xf bank_mask:0xf bound_ctrl:1
	v_mov_b32_e32 v0, v17
	v_mov_b32_e32 v82, v13
	v_add_f32_dpp v66, v66, v66 quad_perm:[2,3,0,1] row_mask:0xf bank_mask:0xf bound_ctrl:1
	v_mov_b32_e32 v84, v9
	v_mov_b32_e32 v86, v5
	v_add_f32_dpp v66, v66, v66 row_half_mirror row_mask:0xf bank_mask:0xf bound_ctrl:1
	s_add_i32 s26, s26, 1
	s_nop 0
	v_add_f32_dpp v66, v66, v66 row_ror:8 row_mask:0xf bank_mask:0xf bound_ctrl:1
	v_pk_fma_f32 v[62:63], v[120:121], v[66:67], v[62:63] op_sel_hi:[1,0,1] neg_lo:[1,0,0] neg_hi:[1,0,0]
	v_pk_fma_f32 v[64:65], v[122:123], v[66:67], v[64:65] op_sel_hi:[1,0,1] neg_lo:[1,0,0] neg_hi:[1,0,0]
	v_pk_mul_f32 v[50:51], v[112:113], v[62:63]
	v_pk_mul_f32 v[46:47], v[104:105], v[62:63]
	v_pk_fma_f32 v[50:51], v[114:115], v[64:65], v[50:51]
	s_waitcnt lgkmcnt(3)
	v_pk_fma_f32 v[66:67], v[14:15], v[58:59], v[46:47] op_sel:[1,0,0]
	v_add_f32_e32 v47, v50, v51
	v_pk_mul_f32 v[48:49], v[106:107], v[64:65]
	v_pk_mul_f32 v[56:57], v[56:57], v[64:65]
	v_add_f32_dpp v68, v47, v47 quad_perm:[1,0,3,2] row_mask:0xf bank_mask:0xf bound_ctrl:1
	v_pk_fma_f32 v[14:15], v[14:15], v[60:61], v[48:49] op_sel:[1,0,0]
	v_pk_fma_f32 v[54:55], v[54:55], v[62:63], v[56:57]
	v_add_f32_dpp v68, v68, v68 quad_perm:[2,3,0,1] row_mask:0xf bank_mask:0xf bound_ctrl:1
	v_add_f32_e32 v92, v54, v55
	s_nop 0
	v_add_f32_dpp v68, v68, v68 row_half_mirror row_mask:0xf bank_mask:0xf bound_ctrl:1
	ds_read_b128 v[46:49], v90 offset:768
	ds_read_b128 v[50:53], v89 offset:4864
	ds_read_b128 v[54:57], v90 offset:4864
	ds_read_b128 v[58:61], v90 offset:8960
	ds_read_b128 v[62:65], v89 offset:17152
	v_add_f32_dpp v68, v68, v68 row_ror:8 row_mask:0xf bank_mask:0xf bound_ctrl:1
	v_pk_fma_f32 v[42:43], v[128:129], v[68:69], v[66:67] op_sel_hi:[1,0,1] neg_lo:[1,0,0] neg_hi:[1,0,0]
	v_pk_fma_f32 v[14:15], v[130:131], v[68:69], v[14:15] op_sel_hi:[1,0,1] neg_lo:[1,0,0] neg_hi:[1,0,0]
	v_pk_mul_f32 v[38:39], v[124:125], v[42:43]
	v_pk_mul_f32 v[28:29], v[28:29], v[14:15]
	v_pk_mul_f32 v[36:37], v[118:119], v[14:15]
	v_pk_fma_f32 v[14:15], v[126:127], v[14:15], v[38:39]
	v_pk_mul_f32 v[34:35], v[116:117], v[42:43]
	v_add_f32_e32 v14, v14, v15
	v_pk_fma_f32 v[26:27], v[26:27], v[42:43], v[28:29]
	s_waitcnt lgkmcnt(7)
	v_pk_fma_f32 v[42:43], v[16:17], v[30:31], v[34:35] op_sel_hi:[0,1,1]
	v_add_f32_dpp v66, v14, v14 quad_perm:[1,0,3,2] row_mask:0xf bank_mask:0xf bound_ctrl:1
	v_pk_fma_f32 v[44:45], v[16:17], v[32:33], v[36:37] op_sel_hi:[0,1,1]
	v_add_f32_e32 v93, v26, v27
	v_add_f32_dpp v66, v66, v66 quad_perm:[2,3,0,1] row_mask:0xf bank_mask:0xf bound_ctrl:1
	ds_read_b128 v[14:17], v90 offset:1024
	ds_read_b128 v[26:29], v89 offset:5120
	ds_read_b128 v[30:33], v90 offset:5120
	ds_read_b128 v[34:37], v90 offset:9216
	ds_read_b128 v[38:41], v89 offset:17408
	v_add_f32_dpp v66, v66, v66 row_half_mirror row_mask:0xf bank_mask:0xf bound_ctrl:1
	s_nop 1
	v_add_f32_dpp v66, v66, v66 row_ror:8 row_mask:0xf bank_mask:0xf bound_ctrl:1
	s_waitcnt lgkmcnt(11)
	v_pk_fma_f32 v[22:23], v[22:23], v[66:67], v[42:43] op_sel_hi:[1,0,1] neg_lo:[1,0,0] neg_hi:[1,0,0]
	v_pk_fma_f32 v[24:25], v[24:25], v[66:67], v[44:45] op_sel_hi:[1,0,1] neg_lo:[1,0,0] neg_hi:[1,0,0]
	s_waitcnt lgkmcnt(7)
	v_pk_mul_f32 v[42:43], v[54:55], v[22:23]
	v_pk_mul_f32 v[20:21], v[20:21], v[24:25]
	v_pk_mul_f32 v[44:45], v[46:47], v[22:23]
	v_pk_mul_f32 v[46:47], v[48:49], v[24:25]
	v_pk_fma_f32 v[18:19], v[18:19], v[22:23], v[20:21]
	v_pk_fma_f32 v[20:21], v[56:57], v[24:25], v[42:43]
	v_pk_fma_f32 v[54:55], v[0:1], v[50:51], v[44:45] op_sel_hi:[0,1,1]
	v_pk_fma_f32 v[56:57], v[0:1], v[52:53], v[46:47] op_sel_hi:[0,1,1]
	v_add_f32_e32 v94, v18, v19
	v_add_f32_e32 v18, v20, v21
	s_nop 0
	s_nop 0
	v_add_f32_dpp v0, v18, v18 quad_perm:[1,0,3,2] row_mask:0xf bank_mask:0xf bound_ctrl:1
	ds_read_b128 v[18:21], v90 offset:1280
	ds_read_b128 v[22:25], v89 offset:5376
	v_add_f32_dpp v0, v0, v0 quad_perm:[2,3,0,1] row_mask:0xf bank_mask:0xf bound_ctrl:1
	ds_read_b128 v[42:45], v90 offset:5376
	ds_read_b128 v[46:49], v90 offset:9472
	v_add_f32_dpp v0, v0, v0 row_half_mirror row_mask:0xf bank_mask:0xf bound_ctrl:1
	ds_read_b128 v[50:53], v89 offset:17664
	s_waitcnt lgkmcnt(11)
	v_add_f32_dpp v0, v0, v0 row_ror:8 row_mask:0xf bank_mask:0xf bound_ctrl:1
	v_pk_fma_f32 v[54:55], v[58:59], v[0:1], v[54:55] op_sel_hi:[1,0,1] neg_lo:[1,0,0] neg_hi:[1,0,0]
	v_pk_fma_f32 v[56:57], v[60:61], v[0:1], v[56:57] op_sel_hi:[1,0,1] neg_lo:[1,0,0] neg_hi:[1,0,0]
	s_waitcnt lgkmcnt(7)
	v_pk_mul_f32 v[30:31], v[30:31], v[54:55]
	v_pk_mul_f32 v[58:59], v[64:65], v[56:57]
	v_pk_mul_f32 v[14:15], v[14:15], v[54:55]
	v_pk_fma_f32 v[54:55], v[62:63], v[54:55], v[58:59]
	v_pk_fma_f32 v[30:31], v[32:33], v[56:57], v[30:31]
	v_pk_fma_f32 v[62:63], v[10:11], v[26:27], v[14:15] op_sel_hi:[0,1,1]
	v_add_f32_e32 v95, v54, v55
	v_add_f32_e32 v14, v30, v31
	ds_write_b128 v91, v[92:95] offset:43008
	v_pk_mul_f32 v[16:17], v[16:17], v[56:57]
	v_add_f32_dpp v0, v14, v14 quad_perm:[1,0,3,2] row_mask:0xf bank_mask:0xf bound_ctrl:1
	v_pk_fma_f32 v[64:65], v[10:11], v[28:29], v[16:17] op_sel_hi:[0,1,1]
	ds_read_b128 v[14:17], v90 offset:1536
	v_add_f32_dpp v0, v0, v0 quad_perm:[2,3,0,1] row_mask:0xf bank_mask:0xf bound_ctrl:1
	ds_read_b128 v[26:29], v89 offset:5632
	ds_read_b128 v[30:33], v90 offset:5632
	v_add_f32_dpp v0, v0, v0 row_half_mirror row_mask:0xf bank_mask:0xf bound_ctrl:1
	ds_read_b128 v[54:57], v90 offset:9728
	ds_read_b128 v[58:61], v89 offset:17920
	v_add_f32_dpp v0, v0, v0 row_ror:8 row_mask:0xf bank_mask:0xf bound_ctrl:1
	s_waitcnt lgkmcnt(12)
	v_pk_fma_f32 v[34:35], v[34:35], v[0:1], v[62:63] op_sel_hi:[1,0,1] neg_lo:[1,0,0] neg_hi:[1,0,0]
	v_pk_fma_f32 v[36:37], v[36:37], v[0:1], v[64:65] op_sel_hi:[1,0,1] neg_lo:[1,0,0] neg_hi:[1,0,0]
	s_waitcnt lgkmcnt(8)
	v_pk_mul_f32 v[42:43], v[42:43], v[34:35]
	v_pk_mul_f32 v[40:41], v[40:41], v[36:37]
	v_pk_mul_f32 v[18:19], v[18:19], v[34:35]
	v_pk_mul_f32 v[20:21], v[20:21], v[36:37]
	v_pk_fma_f32 v[34:35], v[38:39], v[34:35], v[40:41]
	v_pk_fma_f32 v[36:37], v[44:45], v[36:37], v[42:43]
	v_pk_fma_f32 v[62:63], v[10:11], v[22:23], v[18:19] op_sel:[1,0,0]
	v_add_f32_e32 v18, v36, v37
	v_add_f32_e32 v96, v34, v35
	v_pk_fma_f32 v[10:11], v[10:11], v[24:25], v[20:21] op_sel:[1,0,0]
	v_add_f32_dpp v0, v18, v18 quad_perm:[1,0,3,2] row_mask:0xf bank_mask:0xf bound_ctrl:1
	ds_read_b128 v[18:21], v90 offset:1792
	ds_read_b128 v[22:25], v89 offset:5888
	v_add_f32_dpp v0, v0, v0 quad_perm:[2,3,0,1] row_mask:0xf bank_mask:0xf bound_ctrl:1
	ds_read_b128 v[34:37], v90 offset:5888
	ds_read_b128 v[38:41], v90 offset:9984
	v_add_f32_dpp v0, v0, v0 row_half_mirror row_mask:0xf bank_mask:0xf bound_ctrl:1
	ds_read_b128 v[42:45], v89 offset:18176
	s_waitcnt lgkmcnt(12)
	v_add_f32_dpp v0, v0, v0 row_ror:8 row_mask:0xf bank_mask:0xf bound_ctrl:1
	v_pk_fma_f32 v[46:47], v[46:47], v[0:1], v[62:63] op_sel_hi:[1,0,1] neg_lo:[1,0,0] neg_hi:[1,0,0]
	v_pk_fma_f32 v[10:11], v[48:49], v[0:1], v[10:11] op_sel_hi:[1,0,1] neg_lo:[1,0,0] neg_hi:[1,0,0]
	s_waitcnt lgkmcnt(7)
	v_pk_mul_f32 v[30:31], v[30:31], v[46:47]
	v_pk_mul_f32 v[48:49], v[52:53], v[10:11]
	v_pk_mul_f32 v[14:15], v[14:15], v[46:47]
	v_pk_mul_f32 v[16:17], v[16:17], v[10:11]
	v_pk_fma_f32 v[46:47], v[50:51], v[46:47], v[48:49]
	v_pk_fma_f32 v[10:11], v[32:33], v[10:11], v[30:31]
	v_add_f32_e32 v10, v10, v11
	v_add_f32_e32 v97, v46, v47
	v_pk_fma_f32 v[50:51], v[12:13], v[26:27], v[14:15] op_sel_hi:[0,1,1]
	v_add_f32_dpp v0, v10, v10 quad_perm:[1,0,3,2] row_mask:0xf bank_mask:0xf bound_ctrl:1
	v_pk_fma_f32 v[52:53], v[12:13], v[28:29], v[16:17] op_sel_hi:[0,1,1]
	ds_read_b128 v[10:13], v90 offset:2048
	v_add_f32_dpp v0, v0, v0 quad_perm:[2,3,0,1] row_mask:0xf bank_mask:0xf bound_ctrl:1
	ds_read_b128 v[14:17], v89 offset:6144
	ds_read_b128 v[26:29], v90 offset:6144
	v_add_f32_dpp v0, v0, v0 row_half_mirror row_mask:0xf bank_mask:0xf bound_ctrl:1
	ds_read_b128 v[30:33], v90 offset:10240
	ds_read_b128 v[46:49], v89 offset:18432
	v_add_f32_dpp v0, v0, v0 row_ror:8 row_mask:0xf bank_mask:0xf bound_ctrl:1
	s_waitcnt lgkmcnt(11)
	v_pk_fma_f32 v[50:51], v[54:55], v[0:1], v[50:51] op_sel_hi:[1,0,1] neg_lo:[1,0,0] neg_hi:[1,0,0]
	v_pk_fma_f32 v[52:53], v[56:57], v[0:1], v[52:53] op_sel_hi:[1,0,1] neg_lo:[1,0,0] neg_hi:[1,0,0]
	s_waitcnt lgkmcnt(7)
	v_pk_mul_f32 v[34:35], v[34:35], v[50:51]
	v_pk_mul_f32 v[54:55], v[60:61], v[52:53]
	v_pk_mul_f32 v[18:19], v[18:19], v[50:51]
	v_pk_fma_f32 v[50:51], v[58:59], v[50:51], v[54:55]
	v_pk_fma_f32 v[34:35], v[36:37], v[52:53], v[34:35]
	v_pk_fma_f32 v[58:59], v[82:83], v[22:23], v[18:19] op_sel_hi:[0,1,1]
	v_add_f32_e32 v18, v34, v35
	v_add_f32_e32 v98, v50, v51
	v_pk_mul_f32 v[20:21], v[20:21], v[52:53]
	v_add_f32_dpp v0, v18, v18 quad_perm:[1,0,3,2] row_mask:0xf bank_mask:0xf bound_ctrl:1
	v_pk_fma_f32 v[60:61], v[82:83], v[24:25], v[20:21] op_sel_hi:[0,1,1]
	ds_read_b128 v[18:21], v90 offset:2304
	v_add_f32_dpp v0, v0, v0 quad_perm:[2,3,0,1] row_mask:0xf bank_mask:0xf bound_ctrl:1
	ds_read_b128 v[22:25], v89 offset:6400
	ds_read_b128 v[34:37], v90 offset:6400
	v_add_f32_dpp v0, v0, v0 row_half_mirror row_mask:0xf bank_mask:0xf bound_ctrl:1
	ds_read_b128 v[50:53], v90 offset:10496
	ds_read_b128 v[54:57], v89 offset:18688
	v_add_f32_dpp v0, v0, v0 row_ror:8 row_mask:0xf bank_mask:0xf bound_ctrl:1
	s_waitcnt lgkmcnt(11)
	v_pk_fma_f32 v[38:39], v[38:39], v[0:1], v[58:59] op_sel_hi:[1,0,1] neg_lo:[1,0,0] neg_hi:[1,0,0]
	v_pk_fma_f32 v[40:41], v[40:41], v[0:1], v[60:61] op_sel_hi:[1,0,1] neg_lo:[1,0,0] neg_hi:[1,0,0]
	s_waitcnt lgkmcnt(7)
	v_pk_mul_f32 v[26:27], v[26:27], v[38:39]
	v_pk_mul_f32 v[44:45], v[44:45], v[40:41]
	v_pk_mul_f32 v[10:11], v[10:11], v[38:39]
	v_pk_fma_f32 v[38:39], v[42:43], v[38:39], v[44:45]
	v_pk_fma_f32 v[26:27], v[28:29], v[40:41], v[26:27]
	v_pk_fma_f32 v[58:59], v[6:7], v[14:15], v[10:11] op_sel_hi:[0,1,1]
	v_add_f32_e32 v99, v38, v39
	v_add_f32_e32 v10, v26, v27
	ds_write_b128 v91, v[96:99] offset:47104
	v_pk_mul_f32 v[12:13], v[12:13], v[40:41]
	v_add_f32_dpp v0, v10, v10 quad_perm:[1,0,3,2] row_mask:0xf bank_mask:0xf bound_ctrl:1
	v_pk_fma_f32 v[60:61], v[6:7], v[16:17], v[12:13] op_sel_hi:[0,1,1]
	ds_read_b128 v[10:13], v90 offset:2560
	v_add_f32_dpp v0, v0, v0 quad_perm:[2,3,0,1] row_mask:0xf bank_mask:0xf bound_ctrl:1
	ds_read_b128 v[14:17], v89 offset:6656
	ds_read_b128 v[26:29], v90 offset:6656
	v_add_f32_dpp v0, v0, v0 row_half_mirror row_mask:0xf bank_mask:0xf bound_ctrl:1
	ds_read_b128 v[38:41], v90 offset:10752
	ds_read_b128 v[42:45], v89 offset:18944
	v_add_f32_dpp v0, v0, v0 row_ror:8 row_mask:0xf bank_mask:0xf bound_ctrl:1
	s_waitcnt lgkmcnt(12)
	v_pk_fma_f32 v[30:31], v[30:31], v[0:1], v[58:59] op_sel_hi:[1,0,1] neg_lo:[1,0,0] neg_hi:[1,0,0]
	v_pk_fma_f32 v[32:33], v[32:33], v[0:1], v[60:61] op_sel_hi:[1,0,1] neg_lo:[1,0,0] neg_hi:[1,0,0]
	s_waitcnt lgkmcnt(8)
	v_pk_mul_f32 v[34:35], v[34:35], v[30:31]
	v_pk_mul_f32 v[48:49], v[48:49], v[32:33]
	v_pk_mul_f32 v[18:19], v[18:19], v[30:31]
	v_pk_mul_f32 v[20:21], v[20:21], v[32:33]
	v_pk_fma_f32 v[30:31], v[46:47], v[30:31], v[48:49]
	v_pk_fma_f32 v[32:33], v[36:37], v[32:33], v[34:35]
	v_pk_fma_f32 v[58:59], v[6:7], v[22:23], v[18:19] op_sel:[1,0,0]
	v_add_f32_e32 v18, v32, v33
	v_add_f32_e32 v92, v30, v31
	v_pk_fma_f32 v[6:7], v[6:7], v[24:25], v[20:21] op_sel:[1,0,0]
	v_add_f32_dpp v0, v18, v18 quad_perm:[1,0,3,2] row_mask:0xf bank_mask:0xf bound_ctrl:1
	ds_read_b128 v[18:21], v90 offset:2816
	ds_read_b128 v[22:25], v89 offset:6912
	v_add_f32_dpp v0, v0, v0 quad_perm:[2,3,0,1] row_mask:0xf bank_mask:0xf bound_ctrl:1
	ds_read_b128 v[30:33], v90 offset:6912
	ds_read_b128 v[34:37], v90 offset:11008
	v_add_f32_dpp v0, v0, v0 row_half_mirror row_mask:0xf bank_mask:0xf bound_ctrl:1
	ds_read_b128 v[46:49], v89 offset:19200
	s_waitcnt lgkmcnt(12)
	v_add_f32_dpp v0, v0, v0 row_ror:8 row_mask:0xf bank_mask:0xf bound_ctrl:1
	v_pk_fma_f32 v[50:51], v[50:51], v[0:1], v[58:59] op_sel_hi:[1,0,1] neg_lo:[1,0,0] neg_hi:[1,0,0]
	v_pk_fma_f32 v[6:7], v[52:53], v[0:1], v[6:7] op_sel_hi:[1,0,1] neg_lo:[1,0,0] neg_hi:[1,0,0]
	s_waitcnt lgkmcnt(7)
	v_pk_mul_f32 v[26:27], v[26:27], v[50:51]
	v_pk_mul_f32 v[52:53], v[56:57], v[6:7]
	v_pk_mul_f32 v[10:11], v[10:11], v[50:51]
	v_pk_mul_f32 v[12:13], v[12:13], v[6:7]
	v_pk_fma_f32 v[50:51], v[54:55], v[50:51], v[52:53]
	v_pk_fma_f32 v[6:7], v[28:29], v[6:7], v[26:27]
	v_add_f32_e32 v6, v6, v7
	v_add_f32_e32 v93, v50, v51
	v_pk_fma_f32 v[54:55], v[8:9], v[14:15], v[10:11] op_sel_hi:[0,1,1]
	v_add_f32_dpp v0, v6, v6 quad_perm:[1,0,3,2] row_mask:0xf bank_mask:0xf bound_ctrl:1
	v_pk_fma_f32 v[56:57], v[8:9], v[16:17], v[12:13] op_sel_hi:[0,1,1]
	ds_read_b128 v[6:9], v90 offset:3072
	v_add_f32_dpp v0, v0, v0 quad_perm:[2,3,0,1] row_mask:0xf bank_mask:0xf bound_ctrl:1
	ds_read_b128 v[10:13], v89 offset:7168
	ds_read_b128 v[14:17], v90 offset:7168
	v_add_f32_dpp v0, v0, v0 row_half_mirror row_mask:0xf bank_mask:0xf bound_ctrl:1
	ds_read_b128 v[26:29], v90 offset:11264
	ds_read_b128 v[50:53], v89 offset:19456
	v_add_f32_dpp v0, v0, v0 row_ror:8 row_mask:0xf bank_mask:0xf bound_ctrl:1
	s_waitcnt lgkmcnt(11)
	v_pk_fma_f32 v[38:39], v[38:39], v[0:1], v[54:55] op_sel_hi:[1,0,1] neg_lo:[1,0,0] neg_hi:[1,0,0]
	v_pk_fma_f32 v[40:41], v[40:41], v[0:1], v[56:57] op_sel_hi:[1,0,1] neg_lo:[1,0,0] neg_hi:[1,0,0]
	s_waitcnt lgkmcnt(7)
	v_pk_mul_f32 v[30:31], v[30:31], v[38:39]
	v_pk_mul_f32 v[44:45], v[44:45], v[40:41]
	v_pk_mul_f32 v[18:19], v[18:19], v[38:39]
	v_pk_fma_f32 v[38:39], v[42:43], v[38:39], v[44:45]
	v_pk_fma_f32 v[30:31], v[32:33], v[40:41], v[30:31]
	v_pk_fma_f32 v[54:55], v[84:85], v[22:23], v[18:19] op_sel_hi:[0,1,1]
	v_add_f32_e32 v18, v30, v31
	v_add_f32_e32 v94, v38, v39
	v_pk_mul_f32 v[20:21], v[20:21], v[40:41]
	v_add_f32_dpp v0, v18, v18 quad_perm:[1,0,3,2] row_mask:0xf bank_mask:0xf bound_ctrl:1
	v_pk_fma_f32 v[56:57], v[84:85], v[24:25], v[20:21] op_sel_hi:[0,1,1]
	ds_read_b128 v[18:21], v90 offset:3328
	v_add_f32_dpp v0, v0, v0 quad_perm:[2,3,0,1] row_mask:0xf bank_mask:0xf bound_ctrl:1
	ds_read_b128 v[22:25], v89 offset:7424
	ds_read_b128 v[30:33], v90 offset:7424
	v_add_f32_dpp v0, v0, v0 row_half_mirror row_mask:0xf bank_mask:0xf bound_ctrl:1
	ds_read_b128 v[38:41], v90 offset:11520
	ds_read_b128 v[42:45], v89 offset:19712
	v_add_f32_dpp v0, v0, v0 row_ror:8 row_mask:0xf bank_mask:0xf bound_ctrl:1
	s_waitcnt lgkmcnt(11)
	v_pk_fma_f32 v[34:35], v[34:35], v[0:1], v[54:55] op_sel_hi:[1,0,1] neg_lo:[1,0,0] neg_hi:[1,0,0]
	v_pk_fma_f32 v[36:37], v[36:37], v[0:1], v[56:57] op_sel_hi:[1,0,1] neg_lo:[1,0,0] neg_hi:[1,0,0]
	s_waitcnt lgkmcnt(7)
	v_pk_mul_f32 v[14:15], v[14:15], v[34:35]
	v_pk_mul_f32 v[48:49], v[48:49], v[36:37]
	v_pk_mul_f32 v[6:7], v[6:7], v[34:35]
	v_pk_fma_f32 v[34:35], v[46:47], v[34:35], v[48:49]
	v_pk_fma_f32 v[14:15], v[16:17], v[36:37], v[14:15]
	v_pk_fma_f32 v[54:55], v[2:3], v[10:11], v[6:7] op_sel_hi:[0,1,1]
	v_add_f32_e32 v95, v34, v35
	v_add_f32_e32 v6, v14, v15
	ds_write_b128 v91, v[92:95] offset:51200
	v_pk_mul_f32 v[8:9], v[8:9], v[36:37]
	v_add_f32_dpp v0, v6, v6 quad_perm:[1,0,3,2] row_mask:0xf bank_mask:0xf bound_ctrl:1
	v_pk_fma_f32 v[56:57], v[2:3], v[12:13], v[8:9] op_sel_hi:[0,1,1]
	ds_read_b128 v[6:9], v90 offset:3584
	v_add_f32_dpp v0, v0, v0 quad_perm:[2,3,0,1] row_mask:0xf bank_mask:0xf bound_ctrl:1
	ds_read_b128 v[10:13], v89 offset:7680
	ds_read_b128 v[14:17], v90 offset:7680
	v_add_f32_dpp v0, v0, v0 row_half_mirror row_mask:0xf bank_mask:0xf bound_ctrl:1
	ds_read_b128 v[34:37], v90 offset:11776
	ds_read_b128 v[46:49], v89 offset:19968
	v_add_f32_dpp v0, v0, v0 row_ror:8 row_mask:0xf bank_mask:0xf bound_ctrl:1
	s_waitcnt lgkmcnt(12)
	v_pk_fma_f32 v[26:27], v[26:27], v[0:1], v[54:55] op_sel_hi:[1,0,1] neg_lo:[1,0,0] neg_hi:[1,0,0]
	v_pk_fma_f32 v[28:29], v[28:29], v[0:1], v[56:57] op_sel_hi:[1,0,1] neg_lo:[1,0,0] neg_hi:[1,0,0]
	s_waitcnt lgkmcnt(8)
	v_pk_mul_f32 v[30:31], v[30:31], v[26:27]
	v_pk_mul_f32 v[52:53], v[52:53], v[28:29]
	v_pk_mul_f32 v[18:19], v[18:19], v[26:27]
	v_pk_mul_f32 v[20:21], v[20:21], v[28:29]
	v_pk_fma_f32 v[26:27], v[50:51], v[26:27], v[52:53]
	v_pk_fma_f32 v[28:29], v[32:33], v[28:29], v[30:31]
	v_pk_fma_f32 v[54:55], v[2:3], v[22:23], v[18:19] op_sel:[1,0,0]
	v_add_f32_e32 v18, v28, v29
	v_add_f32_e32 v96, v26, v27
	v_pk_fma_f32 v[2:3], v[2:3], v[24:25], v[20:21] op_sel:[1,0,0]
	v_add_f32_dpp v0, v18, v18 quad_perm:[1,0,3,2] row_mask:0xf bank_mask:0xf bound_ctrl:1
	ds_read_b128 v[18:21], v90 offset:3840
	ds_read_b128 v[22:25], v89 offset:7936
	v_add_f32_dpp v0, v0, v0 quad_perm:[2,3,0,1] row_mask:0xf bank_mask:0xf bound_ctrl:1
	ds_read_b128 v[26:29], v90 offset:7936
	ds_read_b128 v[30:33], v90 offset:12032
	v_add_f32_dpp v0, v0, v0 row_half_mirror row_mask:0xf bank_mask:0xf bound_ctrl:1
	ds_read_b128 v[50:53], v89 offset:20224
	s_waitcnt lgkmcnt(12)
	v_add_f32_dpp v0, v0, v0 row_ror:8 row_mask:0xf bank_mask:0xf bound_ctrl:1
	v_pk_fma_f32 v[38:39], v[38:39], v[0:1], v[54:55] op_sel_hi:[1,0,1] neg_lo:[1,0,0] neg_hi:[1,0,0]
	v_pk_fma_f32 v[2:3], v[40:41], v[0:1], v[2:3] op_sel_hi:[1,0,1] neg_lo:[1,0,0] neg_hi:[1,0,0]
	s_waitcnt lgkmcnt(7)
	v_pk_mul_f32 v[14:15], v[14:15], v[38:39]
	v_pk_mul_f32 v[40:41], v[44:45], v[2:3]
	v_pk_mul_f32 v[8:9], v[8:9], v[2:3]
	v_pk_fma_f32 v[2:3], v[16:17], v[2:3], v[14:15]
	v_pk_mul_f32 v[6:7], v[6:7], v[38:39]
	v_add_f32_e32 v0, v2, v3
	v_pk_fma_f32 v[6:7], v[4:5], v[10:11], v[6:7] op_sel_hi:[0,1,1]
	v_pk_fma_f32 v[4:5], v[4:5], v[12:13], v[8:9] op_sel_hi:[0,1,1]
	v_add_f32_dpp v0, v0, v0 quad_perm:[1,0,3,2] row_mask:0xf bank_mask:0xf bound_ctrl:1
	v_pk_fma_f32 v[38:39], v[42:43], v[38:39], v[40:41]
	ds_read_b128 v[108:111], v88 offset:4096
	v_add_f32_dpp v0, v0, v0 quad_perm:[2,3,0,1] row_mask:0xf bank_mask:0xf bound_ctrl:1
	v_add_f32_e32 v97, v38, v39
	ds_read_b128 v[100:103], v88
	v_add_f32_dpp v0, v0, v0 row_half_mirror row_mask:0xf bank_mask:0xf bound_ctrl:1
	ds_read_b128 v[120:123], v88 offset:8192
	ds_read_b128 v[112:115], v88 offset:4352
	v_add_f32_dpp v0, v0, v0 row_ror:8 row_mask:0xf bank_mask:0xf bound_ctrl:1
	s_waitcnt lgkmcnt(10)
	v_pk_fma_f32 v[2:3], v[34:35], v[0:1], v[6:7] op_sel_hi:[1,0,1] neg_lo:[1,0,0] neg_hi:[1,0,0]
	v_pk_fma_f32 v[4:5], v[36:37], v[0:1], v[4:5] op_sel_hi:[1,0,1] neg_lo:[1,0,0] neg_hi:[1,0,0]
	s_waitcnt lgkmcnt(6)
	v_pk_mul_f32 v[8:9], v[26:27], v[2:3]
	v_pk_mul_f32 v[6:7], v[48:49], v[4:5]
	v_pk_mul_f32 v[10:11], v[18:19], v[2:3]
	v_pk_mul_f32 v[12:13], v[20:21], v[4:5]
	v_pk_fma_f32 v[2:3], v[46:47], v[2:3], v[6:7]
	v_pk_fma_f32 v[4:5], v[28:29], v[4:5], v[8:9]
	v_add_f32_e32 v98, v2, v3
	v_add_f32_e32 v2, v4, v5
	v_pk_fma_f32 v[8:9], v[86:87], v[24:25], v[12:13] op_sel_hi:[0,1,1]
	s_nop 0
	v_add_f32_dpp v0, v2, v2 quad_perm:[1,0,3,2] row_mask:0xf bank_mask:0xf bound_ctrl:1
	v_pk_fma_f32 v[6:7], v[86:87], v[22:23], v[10:11] op_sel_hi:[0,1,1]
	ds_read_b128 v[104:107], v88 offset:256
	v_add_f32_dpp v0, v0, v0 quad_perm:[2,3,0,1] row_mask:0xf bank_mask:0xf bound_ctrl:1
	ds_read_b128 v[128:131], v88 offset:8448
	ds_read_b128 v[124:127], v88 offset:4608
	v_add_f32_dpp v0, v0, v0 row_half_mirror row_mask:0xf bank_mask:0xf bound_ctrl:1
	ds_read_b128 v[116:119], v88 offset:512
	s_waitcnt lgkmcnt(9)
	v_add_f32_dpp v0, v0, v0 row_ror:8 row_mask:0xf bank_mask:0xf bound_ctrl:1
	v_pk_fma_f32 v[76:77], v[32:33], v[0:1], v[8:9] op_sel_hi:[1,0,1] neg_lo:[1,0,0] neg_hi:[1,0,0]
	v_pk_fma_f32 v[74:75], v[30:31], v[0:1], v[6:7] op_sel_hi:[1,0,1] neg_lo:[1,0,0] neg_hi:[1,0,0]
	s_waitcnt lgkmcnt(8)
	v_pk_mul_f32 v[2:3], v[52:53], v[76:77]
	s_nop 0
	v_pk_fma_f32 v[2:3], v[50:51], v[74:75], v[2:3]
	s_nop 0
	v_add_f32_e32 v99, v2, v3
	ds_write_b128 v91, v[96:99] offset:55296
	s_and_b32 s2, s26, 1
	s_mul_i32 s3, s2, 0x5400
	v_lshlrev_b32_e32 v91, 2, v87
	v_lshl_add_u32 v91, s2, 14, v91
	s_add_i32 s2, s3, 0
	v_add_u32_e32 v0, s2, v85
	v_add_u32_e32 v89, s2, v83
	v_add_u32_e32 v90, s96, v83
	s_add_i32 s96, s96, 0x3000
	s_cmp_eq_u32 s96, 0x1e800
	s_cselect_b32 s96, 0x20200, s96
	s_cmp_eq_u32 s96, 0x23200
	s_cselect_b32 s96, 0x12800, s96
	v_add_u32_e32 v88, s96, v83
	s_cmpk_eq_i32 s26, 0x110
	s_waitcnt lgkmcnt(0)
	s_cbranch_scc0 .LBB0_1050
	s_barrier
	s_setprio 0
